# sample-row FF1 tile K loop hand-written: fully unrolled, fragment loads of the next 128-wide K step in flight while the current step's MFMAs run (was one load-wait-MFMA round trip per fragment)
# baseline (speedup 1.0000x reference)
; __device__ __forceinline__ void tile32(const bf16_t* __restrict__ A, int lda, const bf16_t* __restrict__ Bt, int ldb, int K, int row0, int col0, int lane, f32x4 (&c)[2][2]) {
;     ...
;   const bf16_t* a0 = A + (size_t)(row0 + i) * lda + kg * 8;
;   const bf16_t* a1 = a0 + (size_t)16 * lda;
;   const bf16_t* b0 = Bt + (size_t)(col0 + i) * ldb + kg * 8;
;   const bf16_t* b1 = b0 + (size_t)16 * ldb;
; #pragma unroll 4
;   for (int k = 0; k < K; k += 32) {
;     const bf16x8 af0 = *(const bf16x8*)(a0 + k), af1 = *(const bf16x8*)(a1 + k), bf0 = *(const bf16x8*)(b0 + k), bf1 = *(const bf16x8*)(b1 + k);
;     c[0][0] = __builtin_amdgcn_mfma_f32_16x16x32_bf16(af0, bf0, c[0][0], 0, 0, 0);
;     c[0][1] = __builtin_amdgcn_mfma_f32_16x16x32_bf16(af0, bf1, c[0][1], 0, 0, 0);
;     c[1][0] = __builtin_amdgcn_mfma_f32_16x16x32_bf16(af1, bf0, c[1][0], 0, 0, 0);
;     c[1][1] = __builtin_amdgcn_mfma_f32_16x16x32_bf16(af1, bf1, c[1][1], 0, 0, 0);
;   }
; __device__ __forceinline__ void sample_ff1(unsigned char* ws, int l) {
;     ...
;     tile32((const bf16_t*)(ws + W_XBF), 1024, (const bf16_t*)(ws + W_FF1) + (size_t)l * 4096 * 1024, 1024, 1024, row0, col0, lane, c);
.LBB0_3788:
	v_lshl_add_u64 v[32:33], v[24:25], 0, v[20:21]
	v_lshl_add_u64 v[34:35], v[22:23], 0, v[20:21]
	s_mov_b32 s0, 0x39c0000
	s_mov_b32 s4, 0x1908000
	v_add_co_u32_e32 v44, vcc, s0, v32
	s_mov_b32 s0, 0x39c8000
	s_mov_b32 s2, 0x1900000
	v_add_co_u32_e64 v50, s[4:5], s4, v34
	v_add_co_u32_e64 v46, s[0:1], s0, v32
	v_add_co_u32_e64 v48, s[2:3], s2, v34
	v_addc_co_u32_e32 v45, vcc, 0, v33, vcc
	v_addc_co_u32_e64 v51, vcc, 0, v35, s[4:5]
	v_addc_co_u32_e64 v47, vcc, 0, v33, s[0:1]
	v_addc_co_u32_e64 v49, vcc, 0, v35, s[2:3]
	global_load_dwordx4 v[52:55], v[44:45], off
	global_load_dwordx4 v[56:59], v[48:49], off
	global_load_dwordx4 v[60:63], v[50:51], off
	global_load_dwordx4 v[64:67], v[46:47], off
	global_load_dwordx4 v[68:71], v[44:45], off offset:64
	global_load_dwordx4 v[72:75], v[48:49], off offset:64
	global_load_dwordx4 v[76:79], v[50:51], off offset:64
	global_load_dwordx4 v[80:83], v[46:47], off offset:64
	global_load_dwordx4 v[84:87], v[44:45], off offset:128
	global_load_dwordx4 v[88:91], v[48:49], off offset:128
	global_load_dwordx4 v[92:95], v[50:51], off offset:128
	global_load_dwordx4 v[96:99], v[46:47], off offset:128
	global_load_dwordx4 v[100:103], v[44:45], off offset:192
	global_load_dwordx4 v[104:107], v[48:49], off offset:192
	global_load_dwordx4 v[108:111], v[50:51], off offset:192
	global_load_dwordx4 v[112:115], v[46:47], off offset:192
	global_load_dwordx4 v[116:119], v[44:45], off offset:256
	global_load_dwordx4 v[120:123], v[48:49], off offset:256
	global_load_dwordx4 v[124:127], v[50:51], off offset:256
	global_load_dwordx4 v[128:131], v[46:47], off offset:256
	global_load_dwordx4 v[132:135], v[44:45], off offset:320
	global_load_dwordx4 v[136:139], v[48:49], off offset:320
	global_load_dwordx4 v[140:143], v[50:51], off offset:320
	global_load_dwordx4 v[144:147], v[46:47], off offset:320
	global_load_dwordx4 v[148:151], v[44:45], off offset:384
	global_load_dwordx4 v[152:155], v[48:49], off offset:384
	global_load_dwordx4 v[156:159], v[50:51], off offset:384
	global_load_dwordx4 v[160:163], v[46:47], off offset:384
	global_load_dwordx4 v[164:167], v[44:45], off offset:448
	global_load_dwordx4 v[168:171], v[48:49], off offset:448
	global_load_dwordx4 v[172:175], v[50:51], off offset:448
	global_load_dwordx4 v[176:179], v[46:47], off offset:448
	s_waitcnt vmcnt(29)
	v_mfma_f32_16x16x32_bf16 v[12:15], v[52:55], v[56:59], v[12:15]
	v_mfma_f32_16x16x32_bf16 v[8:11], v[52:55], v[60:63], v[8:11]
	s_waitcnt vmcnt(28)
	v_mfma_f32_16x16x32_bf16 v[4:7], v[64:67], v[56:59], v[4:7]
	v_mfma_f32_16x16x32_bf16 v[0:3], v[64:67], v[60:63], v[0:3]
	s_waitcnt vmcnt(25)
	v_mfma_f32_16x16x32_bf16 v[12:15], v[68:71], v[72:75], v[12:15]
	v_mfma_f32_16x16x32_bf16 v[8:11], v[68:71], v[76:79], v[8:11]
	s_waitcnt vmcnt(24)
	v_mfma_f32_16x16x32_bf16 v[4:7], v[80:83], v[72:75], v[4:7]
	v_mfma_f32_16x16x32_bf16 v[0:3], v[80:83], v[76:79], v[0:3]
	s_waitcnt vmcnt(21)
	v_mfma_f32_16x16x32_bf16 v[12:15], v[84:87], v[88:91], v[12:15]
	v_mfma_f32_16x16x32_bf16 v[8:11], v[84:87], v[92:95], v[8:11]
	s_waitcnt vmcnt(20)
	v_mfma_f32_16x16x32_bf16 v[4:7], v[96:99], v[88:91], v[4:7]
	v_mfma_f32_16x16x32_bf16 v[0:3], v[96:99], v[92:95], v[0:3]
	s_waitcnt vmcnt(17)
	v_mfma_f32_16x16x32_bf16 v[12:15], v[100:103], v[104:107], v[12:15]
	v_mfma_f32_16x16x32_bf16 v[8:11], v[100:103], v[108:111], v[8:11]
	s_waitcnt vmcnt(16)
	v_mfma_f32_16x16x32_bf16 v[4:7], v[112:115], v[104:107], v[4:7]
	v_mfma_f32_16x16x32_bf16 v[0:3], v[112:115], v[108:111], v[0:3]
	global_load_dwordx4 v[52:55], v[44:45], off offset:512
	global_load_dwordx4 v[56:59], v[48:49], off offset:512
	global_load_dwordx4 v[60:63], v[50:51], off offset:512
	global_load_dwordx4 v[64:67], v[46:47], off offset:512
	global_load_dwordx4 v[68:71], v[44:45], off offset:576
	global_load_dwordx4 v[72:75], v[48:49], off offset:576
	global_load_dwordx4 v[76:79], v[50:51], off offset:576
	global_load_dwordx4 v[80:83], v[46:47], off offset:576
	global_load_dwordx4 v[84:87], v[44:45], off offset:640
	global_load_dwordx4 v[88:91], v[48:49], off offset:640
	global_load_dwordx4 v[92:95], v[50:51], off offset:640
	global_load_dwordx4 v[96:99], v[46:47], off offset:640
	global_load_dwordx4 v[100:103], v[44:45], off offset:704
	global_load_dwordx4 v[104:107], v[48:49], off offset:704
	global_load_dwordx4 v[108:111], v[50:51], off offset:704
	global_load_dwordx4 v[112:115], v[46:47], off offset:704
	s_waitcnt vmcnt(29)
	v_mfma_f32_16x16x32_bf16 v[12:15], v[116:119], v[120:123], v[12:15]
	v_mfma_f32_16x16x32_bf16 v[8:11], v[116:119], v[124:127], v[8:11]
	s_waitcnt vmcnt(28)
	v_mfma_f32_16x16x32_bf16 v[4:7], v[128:131], v[120:123], v[4:7]
	v_mfma_f32_16x16x32_bf16 v[0:3], v[128:131], v[124:127], v[0:3]
	s_waitcnt vmcnt(25)
	v_mfma_f32_16x16x32_bf16 v[12:15], v[132:135], v[136:139], v[12:15]
	v_mfma_f32_16x16x32_bf16 v[8:11], v[132:135], v[140:143], v[8:11]
	s_waitcnt vmcnt(24)
	v_mfma_f32_16x16x32_bf16 v[4:7], v[144:147], v[136:139], v[4:7]
	v_mfma_f32_16x16x32_bf16 v[0:3], v[144:147], v[140:143], v[0:3]
	s_waitcnt vmcnt(21)
	v_mfma_f32_16x16x32_bf16 v[12:15], v[148:151], v[152:155], v[12:15]
	v_mfma_f32_16x16x32_bf16 v[8:11], v[148:151], v[156:159], v[8:11]
	s_waitcnt vmcnt(20)
	v_mfma_f32_16x16x32_bf16 v[4:7], v[160:163], v[152:155], v[4:7]
	v_mfma_f32_16x16x32_bf16 v[0:3], v[160:163], v[156:159], v[0:3]
	s_waitcnt vmcnt(17)
	v_mfma_f32_16x16x32_bf16 v[12:15], v[164:167], v[168:171], v[12:15]
	v_mfma_f32_16x16x32_bf16 v[8:11], v[164:167], v[172:175], v[8:11]
	s_waitcnt vmcnt(16)
; __device__ __forceinline__ void tile32(const bf16_t* __restrict__ A, int lda, const bf16_t* __restrict__ Bt, int ldb, int K, int row0, int col0, int lane, f32x4 (&c)[2][2]) {
;     ...
;   for (int k = 0; k < K; k += 32) {
;     const bf16x8 af0 = *(const bf16x8*)(a0 + k), af1 = *(const bf16x8*)(a1 + k), bf0 = *(const bf16x8*)(b0 + k), bf1 = *(const bf16x8*)(b1 + k);
;     c[0][0] = __builtin_amdgcn_mfma_f32_16x16x32_bf16(af0, bf0, c[0][0], 0, 0, 0);
;     c[0][1] = __builtin_amdgcn_mfma_f32_16x16x32_bf16(af0, bf1, c[0][1], 0, 0, 0);
;     c[1][0] = __builtin_amdgcn_mfma_f32_16x16x32_bf16(af1, bf0, c[1][0], 0, 0, 0);
;     c[1][1] = __builtin_amdgcn_mfma_f32_16x16x32_bf16(af1, bf1, c[1][1], 0, 0, 0);
;   }
	v_mfma_f32_16x16x32_bf16 v[4:7], v[176:179], v[168:171], v[4:7]
	v_mfma_f32_16x16x32_bf16 v[0:3], v[176:179], v[172:175], v[0:3]
	global_load_dwordx4 v[116:119], v[44:45], off offset:768
	global_load_dwordx4 v[120:123], v[48:49], off offset:768
	global_load_dwordx4 v[124:127], v[50:51], off offset:768
	global_load_dwordx4 v[128:131], v[46:47], off offset:768
	global_load_dwordx4 v[132:135], v[44:45], off offset:832
	global_load_dwordx4 v[136:139], v[48:49], off offset:832
	global_load_dwordx4 v[140:143], v[50:51], off offset:832
	global_load_dwordx4 v[144:147], v[46:47], off offset:832
	global_load_dwordx4 v[148:151], v[44:45], off offset:896
	global_load_dwordx4 v[152:155], v[48:49], off offset:896
	global_load_dwordx4 v[156:159], v[50:51], off offset:896
	global_load_dwordx4 v[160:163], v[46:47], off offset:896
	global_load_dwordx4 v[164:167], v[44:45], off offset:960
	global_load_dwordx4 v[168:171], v[48:49], off offset:960
	global_load_dwordx4 v[172:175], v[50:51], off offset:960
	global_load_dwordx4 v[176:179], v[46:47], off offset:960
	s_waitcnt vmcnt(29)
	v_mfma_f32_16x16x32_bf16 v[12:15], v[52:55], v[56:59], v[12:15]
	v_mfma_f32_16x16x32_bf16 v[8:11], v[52:55], v[60:63], v[8:11]
	s_waitcnt vmcnt(28)
	v_mfma_f32_16x16x32_bf16 v[4:7], v[64:67], v[56:59], v[4:7]
	v_mfma_f32_16x16x32_bf16 v[0:3], v[64:67], v[60:63], v[0:3]
	s_waitcnt vmcnt(25)
	v_mfma_f32_16x16x32_bf16 v[12:15], v[68:71], v[72:75], v[12:15]
	v_mfma_f32_16x16x32_bf16 v[8:11], v[68:71], v[76:79], v[8:11]
	s_waitcnt vmcnt(24)
	v_mfma_f32_16x16x32_bf16 v[4:7], v[80:83], v[72:75], v[4:7]
	v_mfma_f32_16x16x32_bf16 v[0:3], v[80:83], v[76:79], v[0:3]
	s_waitcnt vmcnt(21)
	v_mfma_f32_16x16x32_bf16 v[12:15], v[84:87], v[88:91], v[12:15]
	v_mfma_f32_16x16x32_bf16 v[8:11], v[84:87], v[92:95], v[8:11]
	s_waitcnt vmcnt(20)
	v_mfma_f32_16x16x32_bf16 v[4:7], v[96:99], v[88:91], v[4:7]
	v_mfma_f32_16x16x32_bf16 v[0:3], v[96:99], v[92:95], v[0:3]
	s_waitcnt vmcnt(17)
	v_mfma_f32_16x16x32_bf16 v[12:15], v[100:103], v[104:107], v[12:15]
	v_mfma_f32_16x16x32_bf16 v[8:11], v[100:103], v[108:111], v[8:11]
	s_waitcnt vmcnt(16)
	v_mfma_f32_16x16x32_bf16 v[4:7], v[112:115], v[104:107], v[4:7]
	v_mfma_f32_16x16x32_bf16 v[0:3], v[112:115], v[108:111], v[0:3]
	global_load_dwordx4 v[52:55], v[44:45], off offset:1024
	global_load_dwordx4 v[56:59], v[48:49], off offset:1024
	global_load_dwordx4 v[60:63], v[50:51], off offset:1024
	global_load_dwordx4 v[64:67], v[46:47], off offset:1024
	global_load_dwordx4 v[68:71], v[44:45], off offset:1088
	global_load_dwordx4 v[72:75], v[48:49], off offset:1088
	global_load_dwordx4 v[76:79], v[50:51], off offset:1088
	global_load_dwordx4 v[80:83], v[46:47], off offset:1088
	global_load_dwordx4 v[84:87], v[44:45], off offset:1152
	global_load_dwordx4 v[88:91], v[48:49], off offset:1152
	global_load_dwordx4 v[92:95], v[50:51], off offset:1152
	global_load_dwordx4 v[96:99], v[46:47], off offset:1152
	global_load_dwordx4 v[100:103], v[44:45], off offset:1216
	global_load_dwordx4 v[104:107], v[48:49], off offset:1216
	global_load_dwordx4 v[108:111], v[50:51], off offset:1216
	global_load_dwordx4 v[112:115], v[46:47], off offset:1216
	s_waitcnt vmcnt(29)
	v_mfma_f32_16x16x32_bf16 v[12:15], v[116:119], v[120:123], v[12:15]
	v_mfma_f32_16x16x32_bf16 v[8:11], v[116:119], v[124:127], v[8:11]
	s_waitcnt vmcnt(28)
	v_mfma_f32_16x16x32_bf16 v[4:7], v[128:131], v[120:123], v[4:7]
	v_mfma_f32_16x16x32_bf16 v[0:3], v[128:131], v[124:127], v[0:3]
	s_waitcnt vmcnt(25)
	v_mfma_f32_16x16x32_bf16 v[12:15], v[132:135], v[136:139], v[12:15]
	v_mfma_f32_16x16x32_bf16 v[8:11], v[132:135], v[140:143], v[8:11]
	s_waitcnt vmcnt(24)
	v_mfma_f32_16x16x32_bf16 v[4:7], v[144:147], v[136:139], v[4:7]
	v_mfma_f32_16x16x32_bf16 v[0:3], v[144:147], v[140:143], v[0:3]
	s_waitcnt vmcnt(21)
	v_mfma_f32_16x16x32_bf16 v[12:15], v[148:151], v[152:155], v[12:15]
	v_mfma_f32_16x16x32_bf16 v[8:11], v[148:151], v[156:159], v[8:11]
	s_waitcnt vmcnt(20)
	v_mfma_f32_16x16x32_bf16 v[4:7], v[160:163], v[152:155], v[4:7]
	v_mfma_f32_16x16x32_bf16 v[0:3], v[160:163], v[156:159], v[0:3]
	s_waitcnt vmcnt(17)
	v_mfma_f32_16x16x32_bf16 v[12:15], v[164:167], v[168:171], v[12:15]
	v_mfma_f32_16x16x32_bf16 v[8:11], v[164:167], v[172:175], v[8:11]
	s_waitcnt vmcnt(16)
	v_mfma_f32_16x16x32_bf16 v[4:7], v[176:179], v[168:171], v[4:7]
	v_mfma_f32_16x16x32_bf16 v[0:3], v[176:179], v[172:175], v[0:3]
	global_load_dwordx4 v[116:119], v[44:45], off offset:1280
	global_load_dwordx4 v[120:123], v[48:49], off offset:1280
	global_load_dwordx4 v[124:127], v[50:51], off offset:1280
	global_load_dwordx4 v[128:131], v[46:47], off offset:1280
	global_load_dwordx4 v[132:135], v[44:45], off offset:1344
	global_load_dwordx4 v[136:139], v[48:49], off offset:1344
	global_load_dwordx4 v[140:143], v[50:51], off offset:1344
	global_load_dwordx4 v[144:147], v[46:47], off offset:1344
	global_load_dwordx4 v[148:151], v[44:45], off offset:1408
	global_load_dwordx4 v[152:155], v[48:49], off offset:1408
	global_load_dwordx4 v[156:159], v[50:51], off offset:1408
	global_load_dwordx4 v[160:163], v[46:47], off offset:1408
	global_load_dwordx4 v[164:167], v[44:45], off offset:1472
	global_load_dwordx4 v[168:171], v[48:49], off offset:1472
	global_load_dwordx4 v[172:175], v[50:51], off offset:1472
	global_load_dwordx4 v[176:179], v[46:47], off offset:1472
	s_waitcnt vmcnt(29)
	v_mfma_f32_16x16x32_bf16 v[12:15], v[52:55], v[56:59], v[12:15]
	v_mfma_f32_16x16x32_bf16 v[8:11], v[52:55], v[60:63], v[8:11]
	s_waitcnt vmcnt(28)
	v_mfma_f32_16x16x32_bf16 v[4:7], v[64:67], v[56:59], v[4:7]
	v_mfma_f32_16x16x32_bf16 v[0:3], v[64:67], v[60:63], v[0:3]
	s_waitcnt vmcnt(25)
; __device__ __forceinline__ void tile32(const bf16_t* __restrict__ A, int lda, const bf16_t* __restrict__ Bt, int ldb, int K, int row0, int col0, int lane, f32x4 (&c)[2][2]) {
;     ...
;   for (int k = 0; k < K; k += 32) {
;     const bf16x8 af0 = *(const bf16x8*)(a0 + k), af1 = *(const bf16x8*)(a1 + k), bf0 = *(const bf16x8*)(b0 + k), bf1 = *(const bf16x8*)(b1 + k);
;     c[0][0] = __builtin_amdgcn_mfma_f32_16x16x32_bf16(af0, bf0, c[0][0], 0, 0, 0);
;     c[0][1] = __builtin_amdgcn_mfma_f32_16x16x32_bf16(af0, bf1, c[0][1], 0, 0, 0);
;     c[1][0] = __builtin_amdgcn_mfma_f32_16x16x32_bf16(af1, bf0, c[1][0], 0, 0, 0);
;     c[1][1] = __builtin_amdgcn_mfma_f32_16x16x32_bf16(af1, bf1, c[1][1], 0, 0, 0);
;   }
	v_mfma_f32_16x16x32_bf16 v[12:15], v[68:71], v[72:75], v[12:15]
	v_mfma_f32_16x16x32_bf16 v[8:11], v[68:71], v[76:79], v[8:11]
	s_waitcnt vmcnt(24)
	v_mfma_f32_16x16x32_bf16 v[4:7], v[80:83], v[72:75], v[4:7]
	v_mfma_f32_16x16x32_bf16 v[0:3], v[80:83], v[76:79], v[0:3]
	s_waitcnt vmcnt(21)
	v_mfma_f32_16x16x32_bf16 v[12:15], v[84:87], v[88:91], v[12:15]
	v_mfma_f32_16x16x32_bf16 v[8:11], v[84:87], v[92:95], v[8:11]
	s_waitcnt vmcnt(20)
	v_mfma_f32_16x16x32_bf16 v[4:7], v[96:99], v[88:91], v[4:7]
	v_mfma_f32_16x16x32_bf16 v[0:3], v[96:99], v[92:95], v[0:3]
	s_waitcnt vmcnt(17)
	v_mfma_f32_16x16x32_bf16 v[12:15], v[100:103], v[104:107], v[12:15]
	v_mfma_f32_16x16x32_bf16 v[8:11], v[100:103], v[108:111], v[8:11]
	s_waitcnt vmcnt(16)
	v_mfma_f32_16x16x32_bf16 v[4:7], v[112:115], v[104:107], v[4:7]
	v_mfma_f32_16x16x32_bf16 v[0:3], v[112:115], v[108:111], v[0:3]
	global_load_dwordx4 v[52:55], v[44:45], off offset:1536
	global_load_dwordx4 v[56:59], v[48:49], off offset:1536
	global_load_dwordx4 v[60:63], v[50:51], off offset:1536
	global_load_dwordx4 v[64:67], v[46:47], off offset:1536
	global_load_dwordx4 v[68:71], v[44:45], off offset:1600
	global_load_dwordx4 v[72:75], v[48:49], off offset:1600
	global_load_dwordx4 v[76:79], v[50:51], off offset:1600
	global_load_dwordx4 v[80:83], v[46:47], off offset:1600
	global_load_dwordx4 v[84:87], v[44:45], off offset:1664
	global_load_dwordx4 v[88:91], v[48:49], off offset:1664
	global_load_dwordx4 v[92:95], v[50:51], off offset:1664
	global_load_dwordx4 v[96:99], v[46:47], off offset:1664
	global_load_dwordx4 v[100:103], v[44:45], off offset:1728
	global_load_dwordx4 v[104:107], v[48:49], off offset:1728
	global_load_dwordx4 v[108:111], v[50:51], off offset:1728
	global_load_dwordx4 v[112:115], v[46:47], off offset:1728
	s_waitcnt vmcnt(29)
	v_mfma_f32_16x16x32_bf16 v[12:15], v[116:119], v[120:123], v[12:15]
	v_mfma_f32_16x16x32_bf16 v[8:11], v[116:119], v[124:127], v[8:11]
	s_waitcnt vmcnt(28)
	v_mfma_f32_16x16x32_bf16 v[4:7], v[128:131], v[120:123], v[4:7]
	v_mfma_f32_16x16x32_bf16 v[0:3], v[128:131], v[124:127], v[0:3]
	s_waitcnt vmcnt(25)
	v_mfma_f32_16x16x32_bf16 v[12:15], v[132:135], v[136:139], v[12:15]
	v_mfma_f32_16x16x32_bf16 v[8:11], v[132:135], v[140:143], v[8:11]
	s_waitcnt vmcnt(24)
	v_mfma_f32_16x16x32_bf16 v[4:7], v[144:147], v[136:139], v[4:7]
	v_mfma_f32_16x16x32_bf16 v[0:3], v[144:147], v[140:143], v[0:3]
	s_waitcnt vmcnt(21)
	v_mfma_f32_16x16x32_bf16 v[12:15], v[148:151], v[152:155], v[12:15]
	v_mfma_f32_16x16x32_bf16 v[8:11], v[148:151], v[156:159], v[8:11]
	s_waitcnt vmcnt(20)
	v_mfma_f32_16x16x32_bf16 v[4:7], v[160:163], v[152:155], v[4:7]
	v_mfma_f32_16x16x32_bf16 v[0:3], v[160:163], v[156:159], v[0:3]
	s_waitcnt vmcnt(17)
	v_mfma_f32_16x16x32_bf16 v[12:15], v[164:167], v[168:171], v[12:15]
	v_mfma_f32_16x16x32_bf16 v[8:11], v[164:167], v[172:175], v[8:11]
	s_waitcnt vmcnt(16)
	v_mfma_f32_16x16x32_bf16 v[4:7], v[176:179], v[168:171], v[4:7]
	v_mfma_f32_16x16x32_bf16 v[0:3], v[176:179], v[172:175], v[0:3]
	global_load_dwordx4 v[116:119], v[44:45], off offset:1792
	global_load_dwordx4 v[120:123], v[48:49], off offset:1792
	global_load_dwordx4 v[124:127], v[50:51], off offset:1792
	global_load_dwordx4 v[128:131], v[46:47], off offset:1792
	global_load_dwordx4 v[132:135], v[44:45], off offset:1856
	global_load_dwordx4 v[136:139], v[48:49], off offset:1856
	global_load_dwordx4 v[140:143], v[50:51], off offset:1856
	global_load_dwordx4 v[144:147], v[46:47], off offset:1856
	global_load_dwordx4 v[148:151], v[44:45], off offset:1920
	global_load_dwordx4 v[152:155], v[48:49], off offset:1920
	global_load_dwordx4 v[156:159], v[50:51], off offset:1920
	global_load_dwordx4 v[160:163], v[46:47], off offset:1920
	global_load_dwordx4 v[164:167], v[44:45], off offset:1984
	global_load_dwordx4 v[168:171], v[48:49], off offset:1984
	global_load_dwordx4 v[172:175], v[50:51], off offset:1984
	global_load_dwordx4 v[176:179], v[46:47], off offset:1984
	s_waitcnt vmcnt(29)
	v_mfma_f32_16x16x32_bf16 v[12:15], v[52:55], v[56:59], v[12:15]
	v_mfma_f32_16x16x32_bf16 v[8:11], v[52:55], v[60:63], v[8:11]
	s_waitcnt vmcnt(28)
	v_mfma_f32_16x16x32_bf16 v[4:7], v[64:67], v[56:59], v[4:7]
	v_mfma_f32_16x16x32_bf16 v[0:3], v[64:67], v[60:63], v[0:3]
	s_waitcnt vmcnt(25)
	v_mfma_f32_16x16x32_bf16 v[12:15], v[68:71], v[72:75], v[12:15]
	v_mfma_f32_16x16x32_bf16 v[8:11], v[68:71], v[76:79], v[8:11]
	s_waitcnt vmcnt(24)
	v_mfma_f32_16x16x32_bf16 v[4:7], v[80:83], v[72:75], v[4:7]
	v_mfma_f32_16x16x32_bf16 v[0:3], v[80:83], v[76:79], v[0:3]
	s_waitcnt vmcnt(21)
	v_mfma_f32_16x16x32_bf16 v[12:15], v[84:87], v[88:91], v[12:15]
	v_mfma_f32_16x16x32_bf16 v[8:11], v[84:87], v[92:95], v[8:11]
	s_waitcnt vmcnt(20)
; __device__ __forceinline__ void tile32(const bf16_t* __restrict__ A, int lda, const bf16_t* __restrict__ Bt, int ldb, int K, int row0, int col0, int lane, f32x4 (&c)[2][2]) {
;     ...
;     const bf16x8 af0 = *(const bf16x8*)(a0 + k), af1 = *(const bf16x8*)(a1 + k), bf0 = *(const bf16x8*)(b0 + k), bf1 = *(const bf16x8*)(b1 + k);
;     c[0][0] = __builtin_amdgcn_mfma_f32_16x16x32_bf16(af0, bf0, c[0][0], 0, 0, 0);
;     c[0][1] = __builtin_amdgcn_mfma_f32_16x16x32_bf16(af0, bf1, c[0][1], 0, 0, 0);
;     c[1][0] = __builtin_amdgcn_mfma_f32_16x16x32_bf16(af1, bf0, c[1][0], 0, 0, 0);
;     c[1][1] = __builtin_amdgcn_mfma_f32_16x16x32_bf16(af1, bf1, c[1][1], 0, 0, 0);
;   }
; __device__ __forceinline__ void sample_ff1(unsigned char* ws, int l) {
;     ...
;   for (int t = gw; t < 16 * 128; t += nw) {
;     ...
; #pragma unroll
;     for (int rb = 0; rb < 2; ++rb)
; #pragma unroll
;       for (int cc = 0; cc < 2; ++cc)
; #pragma unroll
;         for (int j = 0; j < 4; ++j) {
;           const float a = fmaxf(c[rb][cc][j], 0.f);
;           H[(size_t)(row0 + 16 * rb + (lane >> 4) * 4 + j) * LDH + col0 + 16 * cc + (lane & 15)] = (bf16_t)(cvt_pk_bf16(a * a, 0.f) & 0xffffu);
;         }
	v_mfma_f32_16x16x32_bf16 v[4:7], v[96:99], v[88:91], v[4:7]
	v_mfma_f32_16x16x32_bf16 v[0:3], v[96:99], v[92:95], v[0:3]
	s_waitcnt vmcnt(17)
	v_mfma_f32_16x16x32_bf16 v[12:15], v[100:103], v[104:107], v[12:15]
	v_mfma_f32_16x16x32_bf16 v[8:11], v[100:103], v[108:111], v[8:11]
	s_waitcnt vmcnt(16)
	v_mfma_f32_16x16x32_bf16 v[4:7], v[112:115], v[104:107], v[4:7]
	v_mfma_f32_16x16x32_bf16 v[0:3], v[112:115], v[108:111], v[0:3]
	s_waitcnt vmcnt(13)
	v_mfma_f32_16x16x32_bf16 v[12:15], v[116:119], v[120:123], v[12:15]
	v_mfma_f32_16x16x32_bf16 v[8:11], v[116:119], v[124:127], v[8:11]
	s_waitcnt vmcnt(12)
	v_mfma_f32_16x16x32_bf16 v[4:7], v[128:131], v[120:123], v[4:7]
	v_mfma_f32_16x16x32_bf16 v[0:3], v[128:131], v[124:127], v[0:3]
	s_waitcnt vmcnt(9)
	v_mfma_f32_16x16x32_bf16 v[12:15], v[132:135], v[136:139], v[12:15]
	v_mfma_f32_16x16x32_bf16 v[8:11], v[132:135], v[140:143], v[8:11]
	s_waitcnt vmcnt(8)
	v_mfma_f32_16x16x32_bf16 v[4:7], v[144:147], v[136:139], v[4:7]
	v_mfma_f32_16x16x32_bf16 v[0:3], v[144:147], v[140:143], v[0:3]
	s_waitcnt vmcnt(5)
	v_mfma_f32_16x16x32_bf16 v[12:15], v[148:151], v[152:155], v[12:15]
	v_mfma_f32_16x16x32_bf16 v[8:11], v[148:151], v[156:159], v[8:11]
	s_waitcnt vmcnt(4)
	v_mfma_f32_16x16x32_bf16 v[4:7], v[160:163], v[152:155], v[4:7]
	v_mfma_f32_16x16x32_bf16 v[0:3], v[160:163], v[156:159], v[0:3]
	s_waitcnt vmcnt(1)
	v_mfma_f32_16x16x32_bf16 v[12:15], v[164:167], v[168:171], v[12:15]
	v_mfma_f32_16x16x32_bf16 v[8:11], v[164:167], v[172:175], v[8:11]
	s_waitcnt vmcnt(0)
	v_mfma_f32_16x16x32_bf16 v[4:7], v[176:179], v[168:171], v[4:7]
	v_mfma_f32_16x16x32_bf16 v[0:3], v[176:179], v[172:175], v[0:3]
	s_nop 7
	s_nop 7
	v_or_b32_e32 v31, v16, v28
	v_lshlrev_b32_e32 v16, 6, v26
	v_and_b32_e32 v16, 0x1fc0, v16
	v_max_f32_e32 v12, 0, v12
	v_lshl_add_u64 v[22:23], v[18:19], 0, v[16:17]
	v_mul_f32_e32 v12, v12, v12
	s_movk_i32 s2, 0x2080
	v_cvt_pk_bf16_f32 v12, v12, v17
	v_mad_i64_i32 v[24:25], s[0:1], v31, s2, v[22:23]
	global_store_short v[24:25], v12, off
	s_nop 0
	v_max_f32_e32 v12, 0, v13
	v_mul_f32_e32 v12, v12, v12
	v_cvt_pk_bf16_f32 v16, v12, v17
	v_or_b32_e32 v12, 1, v31
	v_mad_i64_i32 v[12:13], s[0:1], v12, s2, v[22:23]
	v_max_f32_e32 v14, 0, v14
	global_store_short v[12:13], v16, off
	v_mul_f32_e32 v14, v14, v14
	v_or_b32_e32 v16, 2, v31
	v_cvt_pk_bf16_f32 v14, v14, v17
	v_mad_i64_i32 v[32:33], s[0:1], v16, s2, v[22:23]
	global_store_short v[32:33], v14, off
	s_nop 0
	v_max_f32_e32 v14, 0, v15
	v_mul_f32_e32 v14, v14, v14
	s_nop 0
	v_cvt_pk_bf16_f32 v16, v14, v17
	v_or_b32_e32 v14, 3, v31
	v_max_f32_e32 v8, 0, v8
	v_mad_i64_i32 v[14:15], s[0:1], v14, s2, v[22:23]
	v_mul_f32_e32 v8, v8, v8
	global_store_short v[14:15], v16, off
	v_cvt_pk_bf16_f32 v8, v8, v17
	global_store_short v[24:25], v8, off offset:32
	s_nop 0
	v_max_f32_e32 v8, 0, v9
	v_mul_f32_e32 v8, v8, v8
	v_cvt_pk_bf16_f32 v8, v8, v17
	global_store_short v[12:13], v8, off offset:32
	s_nop 0
	v_max_f32_e32 v8, 0, v10
	v_mul_f32_e32 v8, v8, v8
	v_cvt_pk_bf16_f32 v8, v8, v17
	global_store_short v[32:33], v8, off offset:32
	s_nop 0
	v_max_f32_e32 v8, 0, v11
	v_mul_f32_e32 v8, v8, v8
	v_cvt_pk_bf16_f32 v8, v8, v17
	v_max_f32_e32 v4, 0, v4
	global_store_short v[14:15], v8, off offset:32
	v_or_b32_e32 v8, 16, v31
	v_mul_f32_e32 v4, v4, v4
	v_cvt_pk_bf16_f32 v4, v4, v17
	v_mad_i64_i32 v[8:9], s[0:1], v8, s2, v[22:23]
	global_store_short v[8:9], v4, off
	s_nop 0
	v_max_f32_e32 v4, 0, v5
	v_mul_f32_e32 v4, v4, v4
	v_cvt_pk_bf16_f32 v10, v4, v17
	v_or_b32_e32 v4, 17, v31
	v_mad_i64_i32 v[4:5], s[0:1], v4, s2, v[22:23]
	v_max_f32_e32 v6, 0, v6
	global_store_short v[4:5], v10, off
	v_mul_f32_e32 v6, v6, v6
	v_or_b32_e32 v10, 18, v31
	v_cvt_pk_bf16_f32 v6, v6, v17
	v_mad_i64_i32 v[10:11], s[0:1], v10, s2, v[22:23]
	global_store_short v[10:11], v6, off
	s_nop 0
	v_max_f32_e32 v6, 0, v7
	v_mul_f32_e32 v6, v6, v6
	s_nop 0
	v_cvt_pk_bf16_f32 v12, v6, v17
	v_or_b32_e32 v6, 19, v31
	v_max_f32_e32 v0, 0, v0
	v_mad_i64_i32 v[6:7], s[0:1], v6, s2, v[22:23]
	v_mul_f32_e32 v0, v0, v0
	global_store_short v[6:7], v12, off
	v_cvt_pk_bf16_f32 v0, v0, v17
	global_store_short v[8:9], v0, off offset:32
	s_nop 0
	v_max_f32_e32 v0, 0, v1
	v_mul_f32_e32 v0, v0, v0
	v_cvt_pk_bf16_f32 v0, v0, v17
	global_store_short v[4:5], v0, off offset:32
	s_nop 0
	v_max_f32_e32 v0, 0, v2
	v_mul_f32_e32 v0, v0, v0
	v_cvt_pk_bf16_f32 v0, v0, v17
	v_readlane_b32 s0, v255, 8
	global_store_short v[10:11], v0, off offset:32
	s_nop 0
	v_add_u32_e32 v26, s0, v26
	s_movk_i32 s0, 0x7ff
	v_max_f32_e32 v0, 0, v3
	v_cmp_lt_i32_e32 vcc, s0, v26
	v_readlane_b32 s0, v254, 48
	v_mul_f32_e32 v0, v0, v0
	s_or_b64 s[14:15], vcc, s[14:15]
	v_add_u32_e32 v29, s0, v29
	v_cvt_pk_bf16_f32 v0, v0, v17
	global_store_short v[6:7], v0, off offset:32
	v_readlane_b32 s1, v255, 9
	s_andn2_b64 exec, exec, s[14:15]
	s_cbranch_execnz .LBB0_3787
